# baseline (speedup 1.0000x reference)
; #define QK_FENCE() __builtin_amdgcn_sched_barrier(0x406)
; DI void finishSM(f32x16& p0, f32x16& p1, float alpha, float& l_reg, bf16x8& pa0, bf16x8& pa1, bf16x8& pa2, bf16x8& pa3) {
; #pragma unroll
;   for (int r = 0; r < 16; ++r) p1[r] = __builtin_amdgcn_exp2f(p1[r]);
;   float ps = 0;
; #pragma unroll
;   for (int r = 0; r < 16; ++r) ps += p0[r];
; #pragma unroll
;   for (int r = 0; r < 16; ++r) ps += p1[r];
;   { auto rr = __builtin_amdgcn_permlane32_swap(__float_as_uint(ps), __float_as_uint(ps), false, false);
;     ps = __uint_as_float(rr[0]) + __uint_as_float(rr[1]); }
;   l_reg = l_reg * alpha + ps;
;     ...
;   PK4(p0, 0, pa0); PK4(p0, 8, pa1); PK4(p1, 0, pa2); PK4(p1, 8, pa3);
; DI void qkt12(f32x16& p0, f32x16& p1, const char* Kt, const char* Rt, const int* ko, const int* ro, const bf16x8* qr) {
;   { const f32x16 z = {0.f, 0.f, 0.f, 0.f, 0.f, 0.f, 0.f, 0.f, 0.f, 0.f, 0.f, 0.f, 0.f, 0.f, 0.f, 0.f}; p0 = z; p1 = z; }
;   const char* kp[4] = {Kt + ko[0], Kt + ko[1], Kt + ko[2], Kt + ko[3]};
;   const char* rp[4] = {Rt + ro[0], Rt + ro[1], Rt + ro[2], Rt + ro[3]};
;   bf16x8 ka[2], kb[2];
;   ka[0] = *reinterpret_cast<const bf16x8*>(kp[0]); kb[0] = *reinterpret_cast<const bf16x8*>(kp[0] + 8192);
; #pragma unroll
;   for (int d0 = 0; d0 < 12; ++d0) {
;     if (d0 + 1 < 12) { const int d1 = d0 + 1;
;       if (d1 < 8) { ka[d1 & 1] = *reinterpret_cast<const bf16x8*>(kp[d1 & 3] + (d1 >> 2) * 128); kb[d1 & 1] = *reinterpret_cast<const bf16x8*>(kp[d1 & 3] + (d1 >> 2) * 128 + 8192); }
;       else { ka[d1 & 1] = *reinterpret_cast<const bf16x8*>(rp[d1 - 8]); kb[d1 & 1] = *reinterpret_cast<const bf16x8*>(rp[d1 - 8] + 4096); } }
;     QK_FENCE();
;     p0 = __builtin_amdgcn_mfma_f32_32x32x16_bf16(ka[d0 & 1], qr[d0], p0, 0, 0, 0);
;     p1 = __builtin_amdgcn_mfma_f32_32x32x16_bf16(kb[d0 & 1], qr[d0], p1, 0, 0, 0);
;     QK_FENCE();
;   }
.LBB0_122:
	v_sub_co_u32_e64 v64, s[6:7], s61, 1
	s_and_b64 s[6:7], s[6:7], exec
	v_readfirstlane_b32 s2, v64
	s_cselect_b32 s13, 2, s2
	s_mul_i32 s42, s61, 0xa000
	s_add_i32 s45, s42, 16
	v_add_u32_e32 v177, s45, v176
	ds_read_b128 v[64:67], v177 offset:16384
	v_add_u32_e32 v220, s45, v179
	ds_read_b128 v[68:71], v177 offset:24576
	ds_read_b128 v[188:191], v220 offset:16384
	ds_read_b128 v[208:211], v220 offset:24576
	v_add_u32_e32 v221, s45, v180
	v_add_u32_e32 v222, s45, v181
	v_exp_f32_e32 v200, v200
	v_exp_f32_e32 v202, v202
	v_exp_f32_e32 v201, v201
	v_exp_f32_e32 v204, v204
	v_exp_f32_e32 v203, v203
	v_exp_f32_e32 v206, v206
	v_exp_f32_e32 v205, v205
	v_exp_f32_e32 v207, v207
	v_exp_f32_e32 v192, v192
	v_exp_f32_e32 v194, v194
	v_exp_f32_e32 v193, v193
	v_exp_f32_e32 v196, v196
	v_exp_f32_e32 v195, v195
	v_exp_f32_e32 v198, v198
	v_exp_f32_e32 v197, v197
	v_exp_f32_e32 v199, v199
	v_exp_f32_e32 v166, v166
	s_waitcnt lgkmcnt(3)
	v_mfma_f32_32x32x16_bf16 v[80:95], v[64:67], v[134:137], 0
	v_exp_f32_e32 v167, v167
	v_exp_f32_e32 v163, v163
	v_exp_f32_e32 v168, v168
	v_mfma_f32_32x32x16_bf16 v[64:79], v[68:71], v[134:137], 0
	s_add_i32 s2, s42, 0xa000
	s_cmp_lg_u32 s61, 2
	s_cselect_b32 s2, s2, 0
	v_add_u32_e32 v240, s2, v178
	s_add_u32 s0, s82, 0x1bbc0100
	s_addc_u32 s1, s83, 0
	v_lshl_add_u64 v[238:239], v[150:151], 0, s[0:1]
	v_readfirstlane_b32 s2, v240
	s_mov_b32 m0, s2
	v_exp_f32_e32 v169, v169
	global_load_lds_dwordx4 v[238:239], off
	ds_read_b128 v[212:215], v221 offset:16384
	ds_read_b128 v[216:219], v221 offset:24576
	s_waitcnt lgkmcnt(2)
	v_mfma_f32_32x32x16_bf16 v[64:79], v[208:211], v[130:133], v[64:79]
	v_exp_f32_e32 v235, v162
	v_exp_f32_e32 v237, v164
	v_exp_f32_e32 v241, v165
	v_mfma_f32_32x32x16_bf16 v[80:95], v[188:191], v[130:133], v[80:95]
	ds_read_b128 v[188:191], v222 offset:16384
	ds_read_b128 v[208:211], v222 offset:24576
	v_exp_f32_e32 v243, v158
	v_exp_f32_e32 v244, v159
	v_exp_f32_e32 v245, v154
	s_waitcnt lgkmcnt(2)
	v_mfma_f32_32x32x16_bf16 v[64:79], v[216:219], v[126:129], v[64:79]
	v_add_f32_e32 v154, 0, v200
	v_add_f32_e32 v154, v202, v154
	v_add_f32_e32 v154, v201, v154
	v_add_f32_e32 v154, v204, v154
	v_add_f32_e32 v154, v203, v154
	v_add_f32_e32 v154, v206, v154
	v_mfma_f32_32x32x16_bf16 v[80:95], v[212:215], v[126:129], v[80:95]
	v_add_u32_e32 v242, 0x2000, v240
	s_add_u32 s0, s82, 0x1bbe0100
	s_addc_u32 s1, s83, 0
	v_lshl_add_u64 v[238:239], v[150:151], 0, s[0:1]
	v_readfirstlane_b32 s2, v242
	s_mov_b32 m0, s2
	v_add_f32_e32 v154, v205, v154
	global_load_lds_dwordx4 v[238:239], off
	ds_read_b128 v[212:215], v177 offset:16512
	ds_read_b128 v[216:219], v177 offset:24704
	v_add_u32_e32 v177, s45, v182
	v_add_f32_e32 v154, v207, v154
	s_waitcnt lgkmcnt(2)
	v_mfma_f32_32x32x16_bf16 v[64:79], v[208:211], v[114:117], v[64:79]
	v_add_f32_e32 v154, v192, v154
	v_add_f32_e32 v154, v194, v154
	v_add_f32_e32 v154, v193, v154
	v_add_f32_e32 v154, v196, v154
	v_add_f32_e32 v154, v195, v154
	v_add_f32_e32 v154, v198, v154
	v_mfma_f32_32x32x16_bf16 v[80:95], v[188:191], v[114:117], v[80:95]
	ds_read_b128 v[188:191], v220 offset:16512
	ds_read_b128 v[208:211], v220 offset:24704
	v_add_f32_e32 v154, v197, v154
	v_add_f32_e32 v154, v199, v154
	v_exp_f32_e32 v246, v160
	v_add_f32_e32 v154, v166, v154
	s_waitcnt lgkmcnt(2)
	v_mfma_f32_32x32x16_bf16 v[64:79], v[216:219], v[110:113], v[64:79]
	v_exp_f32_e32 v248, v161
	v_add_f32_e32 v154, v167, v154
	v_exp_f32_e32 v249, v156
	v_add_f32_e32 v154, v235, v154
	v_mfma_f32_32x32x16_bf16 v[80:95], v[212:215], v[110:113], v[80:95]
	v_add_u32_e32 v242, 0x4000, v240
	s_add_u32 s0, s82, 0x1bbc0000
	s_addc_u32 s1, s83, 0
	v_lshl_add_u64 v[238:239], v[152:153], 0, s[0:1]
	v_readfirstlane_b32 s2, v242
	s_mov_b32 m0, s2
	v_exp_f32_e32 v250, v157
	global_load_lds_dwordx4 v[238:239], off
	ds_read_b128 v[212:215], v221 offset:16512
	ds_read_b128 v[216:219], v221 offset:24704
	v_add_f32_e32 v154, v163, v154
	s_waitcnt lgkmcnt(2)
	v_mfma_f32_32x32x16_bf16 v[64:79], v[208:211], v[106:109], v[64:79]
	v_add_f32_e32 v154, v246, v154
	v_exp_f32_e32 v251, v155
	v_add_f32_e32 v154, v248, v154
	v_add_f32_e32 v154, v249, v154
	v_add_f32_e32 v154, v250, v154
	v_mfma_f32_32x32x16_bf16 v[80:95], v[188:191], v[106:109], v[80:95]
	ds_read_b128 v[188:191], v222 offset:16512
	ds_read_b128 v[208:211], v222 offset:24704
	v_add_f32_e32 v154, v245, v154
	v_add_f32_e32 v154, v251, v154
	v_add_f32_e32 v154, v168, v154
	v_add_f32_e32 v154, v169, v154
	v_add_f32_e32 v154, v237, v154
	v_add_f32_e32 v154, v241, v154
	s_waitcnt lgkmcnt(2)
	v_mfma_f32_32x32x16_bf16 v[64:79], v[216:219], v[102:105], v[64:79]
	v_add_f32_e32 v154, v243, v154
	v_cvt_pk_bf16_f32 v155, v201, v204
	v_cvt_pk_bf16_f32 v156, v203, v206
	v_cvt_pk_bf16_f32 v157, v205, v207
	v_cvt_pk_bf16_f32 v158, v192, v194
	v_cvt_pk_bf16_f32 v159, v193, v196
	v_mfma_f32_32x32x16_bf16 v[80:95], v[212:215], v[102:105], v[80:95]
	v_add_u32_e32 v242, 0x6000, v240
	s_add_u32 s0, s82, 0x1bbe0000
	s_addc_u32 s1, s83, 0
	v_lshl_add_u64 v[238:239], v[152:153], 0, s[0:1]
	v_readfirstlane_b32 s2, v242
	s_mov_b32 m0, s2
	v_cvt_pk_bf16_f32 v160, v195, v198
	global_load_lds_dwordx4 v[238:239], off
	ds_read_b128 v[212:215], v177 offset:32768
	ds_read_b128 v[216:219], v177 offset:36864
	v_add_u32_e32 v177, s45, v183
	v_cvt_pk_bf16_f32 v161, v197, v199
	s_waitcnt lgkmcnt(2)
; #define SBAR() __builtin_amdgcn_sched_barrier(0)
; template <int OFF> DI s16x4 tr_read(int vb) { s16x4 r; asm volatile("ds_read_b64_tr_b16 %0, %1 offset:%2" : "=&v"(r) : "v"(vb), "i"(OFF) : "memory"); return r; }
; DI void partialSM(f32x16& p0, f32x16& p1, float& m_reg, float& mn, float& alpha) {
;   constexpr float C = ATT_SCALE * 1.4426950408889634f;
;   float pmax = p0[0];
; #pragma unroll
;   for (int r = 1; r < 16; ++r) pmax = fmaxf(pmax, p0[r]);
; #pragma unroll
;   for (int r = 0; r < 16; ++r) pmax = fmaxf(pmax, p1[r]);
;   { auto rr = __builtin_amdgcn_permlane32_swap(__float_as_uint(pmax), __float_as_uint(pmax), false, false);
;     pmax = fmaxf(__uint_as_float(rr[0]), __uint_as_float(rr[1])); }
;   if (__builtin_expect(__all(pmax - m_reg <= ATT_THR / ATT_SCALE), 1)) { mn = m_reg; alpha = 1.f; }
;   else { mn = fmaxf(m_reg, pmax); alpha = __builtin_amdgcn_exp2f((m_reg - mn) * C); m_reg = mn; }
; template <int D0> DI void pv_one(f32x16& od, int vb, bf16x8 pa0, bf16x8 pa1, bf16x8 pa2, bf16x8 pa3) {
;   const s16x4 l0 = tr_read<v_rd_off(D0, 0, 0)>(vb), h0 = tr_read<v_rd_off(D0, 0, 1)>(vb), l1 = tr_read<v_rd_off(D0, 1, 0)>(vb), h1 = tr_read<v_rd_off(D0, 1, 1)>(vb);
;   const s16x4 l2 = tr_read<v_rd_off(D0, 2, 0)>(vb), h2 = tr_read<v_rd_off(D0, 2, 1)>(vb), l3 = tr_read<v_rd_off(D0, 3, 0)>(vb), h3 = tr_read<v_rd_off(D0, 3, 1)>(vb);
;   asm volatile("s_waitcnt lgkmcnt(0)" ::: "memory"); SBAR();
;     ...
;   od = __builtin_amdgcn_mfma_f32_32x32x16_bf16(pa0, PK(l0, h0), od, 0, 0, 0);
;   od = __builtin_amdgcn_mfma_f32_32x32x16_bf16(pa1, PK(l1, h1), od, 0, 0, 0);
;   od = __builtin_amdgcn_mfma_f32_32x32x16_bf16(pa2, PK(l2, h2), od, 0, 0, 0);
;   od = __builtin_amdgcn_mfma_f32_32x32x16_bf16(pa3, PK(l3, h3), od, 0, 0, 0);
;     ...
; }
; DI void pv_d0(f32x16* o, int vb, bf16x8 pa0, bf16x8 pa1, bf16x8 pa2, bf16x8 pa3) {
;   pv_one<0>(o[0], vb, pa0, pa1, pa2, pa3); pv_one<1>(o[1], vb, pa0, pa1, pa2, pa3); pv_one<2>(o[2], vb, pa0, pa1, pa2, pa3); pv_one<3>(o[3], vb, pa0, pa1, pa2, pa3);
	v_mfma_f32_32x32x16_bf16 v[64:79], v[208:211], v[98:101], v[64:79]
	v_permlane32_swap_b32_e32 v155, v157
	v_permlane32_swap_b32_e32 v158, v160
	v_permlane32_swap_b32_e32 v159, v161
	v_cvt_pk_bf16_f32 v162, v166, v167
	v_cvt_pk_bf16_f32 v163, v235, v163
	v_cvt_pk_bf16_f32 v164, v246, v248
	v_mfma_f32_32x32x16_bf16 v[80:95], v[188:191], v[98:101], v[80:95]
	ds_read_b128 v[188:191], v177 offset:32768
	ds_read_b128 v[208:211], v177 offset:36864
	v_add_u32_e32 v177, s45, v184
	v_cvt_pk_bf16_f32 v165, v249, v250
	v_cvt_pk_bf16_f32 v166, v245, v251
	v_cvt_pk_bf16_f32 v167, v168, v169
	v_cvt_pk_bf16_f32 v168, v237, v241
	v_cvt_pk_bf16_f32 v169, v243, v244
	s_waitcnt lgkmcnt(2)
	v_mfma_f32_32x32x16_bf16 v[64:79], v[216:219], v[122:125], v[64:79]
	v_permlane32_swap_b32_e32 v162, v164
	v_permlane32_swap_b32_e32 v163, v165
	v_permlane32_swap_b32_e32 v166, v168
	v_permlane32_swap_b32_e32 v167, v169
	v_mfma_f32_32x32x16_bf16 v[80:95], v[212:215], v[122:125], v[80:95]
	v_add_u32_e32 v242, 0x8000, v240
	s_add_u32 s0, s82, 0x1fb44000
	s_addc_u32 s1, s83, 0
	v_lshl_add_u64 v[238:239], v[148:149], 0, s[0:1]
	v_readfirstlane_b32 s2, v242
	s_mov_b32 m0, s2
	s_nop 0
	global_load_lds_dwordx4 v[238:239], off
	s_movk_i32 s0, 0x410
	s_movk_i32 s1, 0x1800
	ds_read_b128 v[212:215], v177 offset:32768
	ds_read_b128 v[216:219], v177 offset:36864
	v_add_u32_e32 v177, s45, v185
	s_waitcnt lgkmcnt(2)
	v_mfma_f32_32x32x16_bf16 v[64:79], v[208:211], v[142:145], v[64:79]
	v_mfma_f32_32x32x16_bf16 v[80:95], v[188:191], v[142:145], v[80:95]
	ds_read_b128 v[188:191], v177 offset:32768
	ds_read_b128 v[208:211], v177 offset:36864
	s_waitcnt lgkmcnt(2)
	v_mfma_f32_32x32x16_bf16 v[64:79], v[216:219], v[118:121], v[64:79]
	v_mfma_f32_32x32x16_bf16 v[80:95], v[212:215], v[118:121], v[80:95]
	s_waitcnt lgkmcnt(0)
	v_mfma_f32_32x32x16_bf16 v[64:79], v[208:211], v[138:141], v[64:79]
	v_mfma_f32_32x32x16_bf16 v[80:95], v[188:191], v[138:141], v[80:95]
	s_mul_i32 s44, s13, 0xa000
	v_add_u32_e32 v177, s44, v174
	ds_read_b64_tr_b16 v[190:191], v177 offset:0
	ds_read_b64_tr_b16 v[192:193], v177 offset:0x800
	ds_read_b64_tr_b16 v[194:195], v177 offset:0x1000
	ds_read_b64_tr_b16 v[196:197], v177 offset:0x1800
	ds_read_b64_tr_b16 v[198:199], v177 offset:0x2000
	v_add_f32_e32 v188, v244, v154
	v_mov_b32_e32 v189, v188
	v_cvt_pk_bf16_f32 v154, v200, v202
	ds_read_b64_tr_b16 v[200:201], v177 offset:0x2800
	ds_read_b64_tr_b16 v[202:203], v177 offset:0x3000
	ds_read_b64_tr_b16 v[204:205], v177 offset:0x3800
	v_permlane32_swap_b32_e32 v188, v189
	v_permlane32_swap_b32_e32 v154, v156
	s_waitcnt lgkmcnt(6)
	v_max_f32_e32 v235, v81, v81
	v_mfma_f32_32x32x16_bf16 v[0:15], v[154:157], v[190:193], v[0:15]
	ds_read_b64_tr_b16 v[190:191], v177 offset:0x200
	ds_read_b64_tr_b16 v[192:193], v177 offset:0xa00
	v_max_f32_e32 v237, v80, v80
	v_max_f32_e32 v235, v237, v235
	v_max3_f32 v235, v235, v82, v83
	v_max3_f32 v235, v235, v84, v85
	v_max3_f32 v235, v235, v86, v87
	v_max3_f32 v235, v235, v88, v89
	s_waitcnt lgkmcnt(6)
	v_mfma_f32_32x32x16_bf16 v[0:15], v[158:161], v[194:197], v[0:15]
	ds_read_b64_tr_b16 v[194:195], v177 offset:0x1200
	ds_read_b64_tr_b16 v[196:197], v177 offset:0x1a00
	v_max3_f32 v235, v235, v90, v91
	v_max3_f32 v235, v235, v92, v93
	v_max3_f32 v235, v235, v94, v95
	v_max3_f32 v235, v235, v64, v65
	v_max3_f32 v235, v235, v66, v67
	v_max3_f32 v235, v235, v68, v69
	s_waitcnt lgkmcnt(6)
	v_mfma_f32_32x32x16_bf16 v[0:15], v[162:165], v[198:201], v[0:15]
	ds_read_b64_tr_b16 v[198:199], v177 offset:0x2200
	ds_read_b64_tr_b16 v[200:201], v177 offset:0x2a00
	v_max3_f32 v235, v235, v70, v71
	v_max3_f32 v235, v235, v72, v73
	v_max3_f32 v235, v235, v74, v75
	v_max3_f32 v235, v235, v76, v77
	v_max3_f32 v235, v235, v78, v79
	v_mov_b32_e32 v237, v235
	s_waitcnt lgkmcnt(6)
	v_mfma_f32_32x32x16_bf16 v[0:15], v[166:169], v[202:205], v[0:15]
	ds_read_b64_tr_b16 v[202:203], v177 offset:0x3200
	ds_read_b64_tr_b16 v[204:205], v177 offset:0x3a00
	v_permlane32_swap_b32_e32 v235, v237
	v_max_f32_e32 v237, v237, v237
	v_max_f32_e32 v235, v235, v235
	s_waitcnt lgkmcnt(6)
	v_mfma_f32_32x32x16_bf16 v[48:63], v[154:157], v[190:193], v[48:63]
	ds_read_b64_tr_b16 v[190:191], v177 offset:0x400
	ds_read_b64_tr_b16 v[192:193], v177 offset:0xc00
	s_waitcnt lgkmcnt(6)
	v_mfma_f32_32x32x16_bf16 v[48:63], v[158:161], v[194:197], v[48:63]
	ds_read_b64_tr_b16 v[194:195], v177 offset:0x1400
	ds_read_b64_tr_b16 v[196:197], v177 offset:0x1c00
	s_waitcnt lgkmcnt(6)
	v_mfma_f32_32x32x16_bf16 v[48:63], v[162:165], v[198:201], v[48:63]
	ds_read_b64_tr_b16 v[198:199], v177 offset:0x2400
	ds_read_b64_tr_b16 v[200:201], v177 offset:0x2c00
	s_waitcnt lgkmcnt(6)
	v_mfma_f32_32x32x16_bf16 v[48:63], v[166:169], v[202:205], v[48:63]
	ds_read_b64_tr_b16 v[202:203], v177 offset:0x3400
	ds_read_b64_tr_b16 v[204:205], v177 offset:0x3c00
	s_waitcnt lgkmcnt(6)
	v_mfma_f32_32x32x16_bf16 v[32:47], v[154:157], v[190:193], v[32:47]
	ds_read_b64_tr_b16 v[190:191], v177 offset:0x600
	ds_read_b64_tr_b16 v[192:193], v177 offset:0xe00
	s_waitcnt lgkmcnt(6)
	v_mfma_f32_32x32x16_bf16 v[32:47], v[158:161], v[194:197], v[32:47]
	ds_read_b64_tr_b16 v[194:195], v177 offset:0x1600
	ds_read_b64_tr_b16 v[196:197], v177 offset:0x1e00
	s_waitcnt lgkmcnt(6)
	v_mfma_f32_32x32x16_bf16 v[32:47], v[162:165], v[198:201], v[32:47]
	ds_read_b64_tr_b16 v[198:199], v177 offset:0x2600
	ds_read_b64_tr_b16 v[200:201], v177 offset:0x2e00
	s_waitcnt lgkmcnt(6)
	v_mfma_f32_32x32x16_bf16 v[32:47], v[166:169], v[202:205], v[32:47]
	ds_read_b64_tr_b16 v[202:203], v177 offset:0x3600
	ds_read_b64_tr_b16 v[204:205], v177 offset:0x3e00
	s_waitcnt vmcnt(0)
	s_waitcnt lgkmcnt(0)
	s_barrier
	v_mfma_f32_32x32x16_bf16 v[16:31], v[154:157], v[190:193], v[16:31]
	v_mfma_f32_32x32x16_bf16 v[16:31], v[158:161], v[194:197], v[16:31]
	v_max_f32_e32 v160, v235, v237
	v_sub_f32_e32 v235, v160, v187
	v_mfma_f32_32x32x16_bf16 v[16:31], v[162:165], v[198:201], v[16:31]
	v_mfma_f32_32x32x16_bf16 v[16:31], v[166:169], v[202:205], v[16:31]
	v_cmp_ge_f32_e32 vcc, s65, v235
	s_cmp_eq_u64 vcc, exec
	s_waitcnt vmcnt(0)
	s_cselect_b64 s[38:39], -1, 0
	s_add_i32 s2, s12, -1
	s_cmp_ge_u32 s2, s52
	v_lshl_add_u64 v[158:159], v[150:151], 0, s[82:83]
	v_lshl_add_u64 v[156:157], v[152:153], 0, s[82:83]
	v_lshl_add_u64 v[154:155], v[148:149], 0, s[82:83]

; #define QK_FENCE() __builtin_amdgcn_sched_barrier(0x406)
; DI void partialSM(f32x16& p0, f32x16& p1, float& m_reg, float& mn, float& alpha) {
;     ...
;   else { mn = fmaxf(m_reg, pmax); alpha = __builtin_amdgcn_exp2f((m_reg - mn) * C); m_reg = mn; }
;   const float mnC = -mn * C;
; #pragma unroll
;   for (int r = 0; r < 16; ++r) p0[r] = fmaf(p0[r], C, mnC);
; #pragma unroll
;   for (int r = 0; r < 16; ++r) p1[r] = fmaf(p1[r], C, mnC);
; #pragma unroll
;   for (int r = 0; r < 16; ++r) p0[r] = __builtin_amdgcn_exp2f(p0[r]);
; }
; DI void qkt12(f32x16& p0, f32x16& p1, const char* Kt, const char* Rt, const int* ko, const int* ro, const bf16x8* qr) {
;   { const f32x16 z = {0.f, 0.f, 0.f, 0.f, 0.f, 0.f, 0.f, 0.f, 0.f, 0.f, 0.f, 0.f, 0.f, 0.f, 0.f, 0.f}; p0 = z; p1 = z; }
;   const char* kp[4] = {Kt + ko[0], Kt + ko[1], Kt + ko[2], Kt + ko[3]};
;   const char* rp[4] = {Rt + ro[0], Rt + ro[1], Rt + ro[2], Rt + ro[3]};
;   bf16x8 ka[2], kb[2];
;   ka[0] = *reinterpret_cast<const bf16x8*>(kp[0]); kb[0] = *reinterpret_cast<const bf16x8*>(kp[0] + 8192);
; #pragma unroll
;   for (int d0 = 0; d0 < 12; ++d0) {
;     if (d0 + 1 < 12) { const int d1 = d0 + 1;
;       if (d1 < 8) { ka[d1 & 1] = *reinterpret_cast<const bf16x8*>(kp[d1 & 3] + (d1 >> 2) * 128); kb[d1 & 1] = *reinterpret_cast<const bf16x8*>(kp[d1 & 3] + (d1 >> 2) * 128 + 8192); }
;       else { ka[d1 & 1] = *reinterpret_cast<const bf16x8*>(rp[d1 - 8]); kb[d1 & 1] = *reinterpret_cast<const bf16x8*>(rp[d1 - 8] + 4096); } }
;     QK_FENCE();
;     p0 = __builtin_amdgcn_mfma_f32_32x32x16_bf16(ka[d0 & 1], qr[d0], p0, 0, 0, 0);
;     p1 = __builtin_amdgcn_mfma_f32_32x32x16_bf16(kb[d0 & 1], qr[d0], p1, 0, 0, 0);
;     QK_FENCE();
;   }
.LBB0_128:
	s_add_i32 s2, s12, -1
	s_cmp_ge_u32 s2, s52
	s_cbranch_scc1 .Lattn_bb2_nodma
	v_cndmask_b32_e64 v160, v160, v187, s[38:39]
	s_add_i32 s2, s42, 0xa000
	s_cmp_lg_u32 s61, 2
	s_cselect_b32 s2, s2, 0
	s_add_i32 s6, s2, 16
	v_add_u32_e32 v213, s6, v176
	ds_read_b128 v[222:225], v213 offset:16384
	v_add_u32_e32 v230, s6, v179
	ds_read_b128 v[226:229], v213 offset:24576
	ds_read_b128 v[214:217], v230 offset:16384
	ds_read_b128 v[218:221], v230 offset:24576
	v_add_u32_e32 v231, s6, v180
	v_add_u32_e32 v234, s6, v181
	v_mul_f32_e32 v197, 0xbdd53b94, v160
	v_fmamk_f32 v161, v94, 0x3dd53b94, v197
	v_fmamk_f32 v194, v80, 0x3dd53b94, v197
	v_fmamk_f32 v196, v81, 0x3dd53b94, v197
	v_fmamk_f32 v192, v82, 0x3dd53b94, v197
	v_fmamk_f32 v195, v83, 0x3dd53b94, v197
	v_fmamk_f32 v187, v84, 0x3dd53b94, v197
	v_fmamk_f32 v193, v85, 0x3dd53b94, v197
	v_fmamk_f32 v169, v86, 0x3dd53b94, v197
	v_fmamk_f32 v190, v87, 0x3dd53b94, v197
	v_fmamk_f32 v166, v88, 0x3dd53b94, v197
	v_fmamk_f32 v168, v89, 0x3dd53b94, v197
	v_fmamk_f32 v164, v90, 0x3dd53b94, v197
	v_fmamk_f32 v167, v91, 0x3dd53b94, v197
	v_fmamk_f32 v162, v92, 0x3dd53b94, v197
	v_fmamk_f32 v165, v93, 0x3dd53b94, v197
	v_fmamk_f32 v163, v95, 0x3dd53b94, v197
	v_fmamk_f32 v208, v74, 0x3dd53b94, v197
	v_fmamk_f32 v209, v75, 0x3dd53b94, v197
	v_fmamk_f32 v198, v64, 0x3dd53b94, v197
	v_fmamk_f32 v199, v65, 0x3dd53b94, v197
	v_fmamk_f32 v200, v66, 0x3dd53b94, v197
	v_fmamk_f32 v201, v67, 0x3dd53b94, v197
	v_fmamk_f32 v202, v68, 0x3dd53b94, v197
	v_fmamk_f32 v203, v69, 0x3dd53b94, v197
	v_fmamk_f32 v204, v70, 0x3dd53b94, v197
	v_fmamk_f32 v205, v71, 0x3dd53b94, v197
	v_fmamk_f32 v206, v72, 0x3dd53b94, v197
	v_fmamk_f32 v207, v73, 0x3dd53b94, v197
	v_fmamk_f32 v210, v76, 0x3dd53b94, v197
	v_fmamk_f32 v211, v77, 0x3dd53b94, v197
	v_fmamk_f32 v212, v78, 0x3dd53b94, v197
	v_fmac_f32_e32 v197, 0x3dd53b94, v79
	v_exp_f32_e32 v161, v161
	s_waitcnt lgkmcnt(3)
	v_mfma_f32_32x32x16_bf16 v[80:95], v[222:225], v[134:137], 0
	v_exp_f32_e32 v194, v194
	v_exp_f32_e32 v196, v196
	v_exp_f32_e32 v192, v192
	s_waitcnt lgkmcnt(2)
	v_mfma_f32_32x32x16_bf16 v[64:79], v[226:229], v[134:137], 0
	v_add_u32_e32 v240, s44, v178
	v_exp_f32_e32 v195, v195
	v_readfirstlane_b32 s2, v240
	s_mov_b64 s[0:1], 0x1bc00100
	v_lshl_add_u64 v[238:239], v[158:159], 0, s[0:1]
	s_mov_b32 m0, s2
	v_exp_f32_e32 v187, v187
	global_load_lds_dwordx4 v[238:239], off
	ds_read_b128 v[222:225], v231 offset:16384
	ds_read_b128 v[226:229], v231 offset:24576
	s_waitcnt lgkmcnt(3)
	v_mfma_f32_32x32x16_bf16 v[80:95], v[214:217], v[130:133], v[80:95]
	v_exp_f32_e32 v193, v193
	v_exp_f32_e32 v169, v169
	v_exp_f32_e32 v190, v190
	s_waitcnt lgkmcnt(2)
	v_mfma_f32_32x32x16_bf16 v[64:79], v[218:221], v[130:133], v[64:79]
	ds_read_b128 v[214:217], v234 offset:16384
	ds_read_b128 v[218:221], v234 offset:24576
	v_exp_f32_e32 v166, v166
	v_exp_f32_e32 v168, v168
	v_exp_f32_e32 v164, v164
	s_waitcnt lgkmcnt(3)
	v_mfma_f32_32x32x16_bf16 v[80:95], v[222:225], v[126:129], v[80:95]
	v_exp_f32_e32 v167, v167
	v_exp_f32_e32 v162, v162
	v_exp_f32_e32 v165, v165
	s_waitcnt lgkmcnt(2)
	v_mfma_f32_32x32x16_bf16 v[64:79], v[226:229], v[126:129], v[64:79]
	v_add_u32_e32 v242, 0x2000, v240
	s_mov_b64 s[0:1], 0x1bc20100
	v_lshl_add_u64 v[238:239], v[158:159], 0, s[0:1]
	v_readfirstlane_b32 s2, v242
	s_mov_b32 m0, s2
	v_exp_f32_e32 v163, v163
	global_load_lds_dwordx4 v[238:239], off
	ds_read_b128 v[222:225], v213 offset:16512
	ds_read_b128 v[226:229], v213 offset:24704
	v_add_u32_e32 v213, s6, v182
	s_waitcnt lgkmcnt(3)
	v_mfma_f32_32x32x16_bf16 v[80:95], v[214:217], v[114:117], v[80:95]
	v_exp_f32_e32 v198, v198
	v_exp_f32_e32 v199, v199
	v_exp_f32_e32 v200, v200
	s_waitcnt lgkmcnt(2)
	v_mfma_f32_32x32x16_bf16 v[64:79], v[218:221], v[114:117], v[64:79]
	ds_read_b128 v[214:217], v230 offset:16512
	ds_read_b128 v[218:221], v230 offset:24704
	v_exp_f32_e32 v201, v201
	v_exp_f32_e32 v202, v202
	v_exp_f32_e32 v203, v203
	s_waitcnt lgkmcnt(3)
	v_mfma_f32_32x32x16_bf16 v[80:95], v[222:225], v[110:113], v[80:95]
	v_exp_f32_e32 v204, v204
	v_exp_f32_e32 v205, v205
	v_exp_f32_e32 v206, v206
	s_waitcnt lgkmcnt(2)
	v_mfma_f32_32x32x16_bf16 v[64:79], v[226:229], v[110:113], v[64:79]
	v_add_u32_e32 v242, 0x4000, v240
	s_mov_b64 s[0:1], 0x1bc00000
	v_lshl_add_u64 v[238:239], v[156:157], 0, s[0:1]
	v_readfirstlane_b32 s2, v242
	s_mov_b32 m0, s2
	v_exp_f32_e32 v207, v207
	global_load_lds_dwordx4 v[238:239], off
	ds_read_b128 v[222:225], v231 offset:16512
	ds_read_b128 v[226:229], v231 offset:24704
	s_waitcnt lgkmcnt(3)
	v_mfma_f32_32x32x16_bf16 v[80:95], v[214:217], v[106:109], v[80:95]
	v_exp_f32_e32 v210, v210
	v_exp_f32_e32 v211, v211
	v_exp_f32_e32 v212, v212
	s_waitcnt lgkmcnt(2)
	v_mfma_f32_32x32x16_bf16 v[64:79], v[218:221], v[106:109], v[64:79]
	ds_read_b128 v[214:217], v234 offset:16512
	ds_read_b128 v[218:221], v234 offset:24704
	v_exp_f32_e32 v235, v208
	v_exp_f32_e32 v237, v197
	v_add_f32_e32 v197, 0, v194
	v_add_f32_e32 v197, v196, v197
	s_waitcnt lgkmcnt(3)
	v_mfma_f32_32x32x16_bf16 v[80:95], v[222:225], v[102:105], v[80:95]
	v_add_f32_e32 v197, v192, v197
	v_add_f32_e32 v197, v195, v197
	v_add_f32_e32 v197, v187, v197
	v_add_f32_e32 v197, v193, v197
	v_add_f32_e32 v197, v169, v197
	v_add_f32_e32 v197, v190, v197
	s_waitcnt lgkmcnt(2)
	v_mfma_f32_32x32x16_bf16 v[64:79], v[226:229], v[102:105], v[64:79]
	v_add_u32_e32 v242, 0x6000, v240
	s_mov_b64 s[0:1], 0x1bc20000
	v_lshl_add_u64 v[238:239], v[156:157], 0, s[0:1]
	v_readfirstlane_b32 s2, v242
	s_mov_b32 m0, s2
	v_add_f32_e32 v197, v166, v197
	global_load_lds_dwordx4 v[238:239], off
	ds_read_b128 v[222:225], v213 offset:32768
	ds_read_b128 v[226:229], v213 offset:36864
	v_add_u32_e32 v213, s6, v183
	v_add_f32_e32 v197, v168, v197
	s_waitcnt lgkmcnt(3)
; #define SBAR() __builtin_amdgcn_sched_barrier(0)
; template <int OFF> DI s16x4 tr_read(int vb) { s16x4 r; asm volatile("ds_read_b64_tr_b16 %0, %1 offset:%2" : "=&v"(r) : "v"(vb), "i"(OFF) : "memory"); return r; }
; DI void finishSM(f32x16& p0, f32x16& p1, float alpha, float& l_reg, bf16x8& pa0, bf16x8& pa1, bf16x8& pa2, bf16x8& pa3) {
; #pragma unroll
;   for (int r = 0; r < 16; ++r) p1[r] = __builtin_amdgcn_exp2f(p1[r]);
;   float ps = 0;
; #pragma unroll
;   for (int r = 0; r < 16; ++r) ps += p0[r];
; #pragma unroll
;   for (int r = 0; r < 16; ++r) ps += p1[r];
;   { auto rr = __builtin_amdgcn_permlane32_swap(__float_as_uint(ps), __float_as_uint(ps), false, false);
;     ps = __uint_as_float(rr[0]) + __uint_as_float(rr[1]); }
;   l_reg = l_reg * alpha + ps;
;     ...
;   PK4(p0, 0, pa0); PK4(p0, 8, pa1); PK4(p1, 0, pa2); PK4(p1, 8, pa3);
;     ...
; }
; template <int D0> DI void pv_one(f32x16& od, int vb, bf16x8 pa0, bf16x8 pa1, bf16x8 pa2, bf16x8 pa3) {
;   const s16x4 l0 = tr_read<v_rd_off(D0, 0, 0)>(vb), h0 = tr_read<v_rd_off(D0, 0, 1)>(vb), l1 = tr_read<v_rd_off(D0, 1, 0)>(vb), h1 = tr_read<v_rd_off(D0, 1, 1)>(vb);
;   const s16x4 l2 = tr_read<v_rd_off(D0, 2, 0)>(vb), h2 = tr_read<v_rd_off(D0, 2, 1)>(vb), l3 = tr_read<v_rd_off(D0, 3, 0)>(vb), h3 = tr_read<v_rd_off(D0, 3, 1)>(vb);
;   asm volatile("s_waitcnt lgkmcnt(0)" ::: "memory"); SBAR();
;     ...
;   od = __builtin_amdgcn_mfma_f32_32x32x16_bf16(pa0, PK(l0, h0), od, 0, 0, 0);
;   od = __builtin_amdgcn_mfma_f32_32x32x16_bf16(pa1, PK(l1, h1), od, 0, 0, 0);
;   od = __builtin_amdgcn_mfma_f32_32x32x16_bf16(pa2, PK(l2, h2), od, 0, 0, 0);
;   od = __builtin_amdgcn_mfma_f32_32x32x16_bf16(pa3, PK(l3, h3), od, 0, 0, 0);
;     ...
; }
; DI void pv_d0(f32x16* o, int vb, bf16x8 pa0, bf16x8 pa1, bf16x8 pa2, bf16x8 pa3) {
;   pv_one<0>(o[0], vb, pa0, pa1, pa2, pa3); pv_one<1>(o[1], vb, pa0, pa1, pa2, pa3); pv_one<2>(o[2], vb, pa0, pa1, pa2, pa3); pv_one<3>(o[3], vb, pa0, pa1, pa2, pa3);
	v_mfma_f32_32x32x16_bf16 v[80:95], v[214:217], v[98:101], v[80:95]
	v_add_f32_e32 v197, v164, v197
	v_add_f32_e32 v197, v167, v197
	v_add_f32_e32 v197, v162, v197
	v_add_f32_e32 v197, v165, v197
	v_add_f32_e32 v197, v161, v197
	v_add_f32_e32 v197, v163, v197
	s_waitcnt lgkmcnt(2)
	v_mfma_f32_32x32x16_bf16 v[64:79], v[218:221], v[98:101], v[64:79]
	ds_read_b128 v[214:217], v213 offset:32768
	ds_read_b128 v[218:221], v213 offset:36864
	v_add_u32_e32 v213, s6, v184
	v_add_f32_e32 v197, v198, v197
	v_add_f32_e32 v197, v199, v197
	v_add_f32_e32 v197, v200, v197
	v_add_f32_e32 v197, v201, v197
	v_add_f32_e32 v197, v202, v197
	s_waitcnt lgkmcnt(3)
	v_mfma_f32_32x32x16_bf16 v[80:95], v[222:225], v[122:125], v[80:95]
	v_add_f32_e32 v197, v203, v197
	v_add_f32_e32 v197, v204, v197
	v_exp_f32_e32 v241, v209
	v_add_f32_e32 v197, v205, v197
	v_add_f32_e32 v197, v206, v197
	s_waitcnt lgkmcnt(2)
	v_mfma_f32_32x32x16_bf16 v[64:79], v[226:229], v[122:125], v[64:79]
	v_add_u32_e32 v242, 0x8000, v240
	s_mov_b64 s[0:1], 0x1fb46000
	v_lshl_add_u64 v[238:239], v[154:155], 0, s[0:1]
	v_readfirstlane_b32 s2, v242
	s_mov_b32 m0, s2
	v_add_f32_e32 v197, v207, v197
	global_load_lds_dwordx4 v[238:239], off
	s_movk_i32 s0, 0x410
	s_movk_i32 s1, 0x1800
	ds_read_b128 v[222:225], v213 offset:32768
	ds_read_b128 v[226:229], v213 offset:36864
	v_add_u32_e32 v213, s6, v185
	v_add_f32_e32 v197, v235, v197
	s_waitcnt lgkmcnt(3)
	v_mfma_f32_32x32x16_bf16 v[80:95], v[214:217], v[142:145], v[80:95]
	v_add_f32_e32 v197, v241, v197
	v_add_f32_e32 v197, v210, v197
	v_add_f32_e32 v197, v211, v197
	v_add_f32_e32 v197, v212, v197
	v_add_f32_e32 v208, v237, v197
	v_mov_b32_e32 v209, v208
	s_waitcnt lgkmcnt(2)
	v_mfma_f32_32x32x16_bf16 v[64:79], v[218:221], v[142:145], v[64:79]
	ds_read_b128 v[214:217], v213 offset:32768
	ds_read_b128 v[218:221], v213 offset:36864
	v_permlane32_swap_b32_e32 v208, v209
	v_cvt_pk_bf16_f32 v194, v194, v196
	v_cvt_pk_bf16_f32 v195, v192, v195
	v_cvt_pk_bf16_f32 v196, v187, v193
	v_cvt_pk_bf16_f32 v197, v169, v190
	v_cvt_pk_bf16_f32 v166, v166, v168
	s_waitcnt lgkmcnt(3)
	v_mfma_f32_32x32x16_bf16 v[80:95], v[222:225], v[118:121], v[80:95]
	v_cvt_pk_bf16_f32 v167, v164, v167
	v_cvt_pk_bf16_f32 v168, v162, v165
	v_cvt_pk_bf16_f32 v169, v161, v163
	v_cvt_pk_bf16_f32 v162, v198, v199
	v_cvt_pk_bf16_f32 v163, v200, v201
	v_cvt_pk_bf16_f32 v164, v202, v203
	s_waitcnt lgkmcnt(2)
	v_mfma_f32_32x32x16_bf16 v[64:79], v[226:229], v[118:121], v[64:79]
	v_cvt_pk_bf16_f32 v165, v204, v205
	v_cvt_pk_bf16_f32 v198, v206, v207
	v_cvt_pk_bf16_f32 v199, v235, v241
	v_cvt_pk_bf16_f32 v200, v210, v211
	v_cvt_pk_bf16_f32 v201, v212, v237
	v_permlane32_swap_b32_e32 v194, v196
	s_waitcnt lgkmcnt(1)
	v_mfma_f32_32x32x16_bf16 v[80:95], v[214:217], v[138:141], v[80:95]
	v_permlane32_swap_b32_e32 v195, v197
	v_permlane32_swap_b32_e32 v166, v168
	v_permlane32_swap_b32_e32 v167, v169
	v_permlane32_swap_b32_e32 v162, v164
	v_permlane32_swap_b32_e32 v163, v165
	v_permlane32_swap_b32_e32 v198, v200
	s_waitcnt lgkmcnt(0)
	v_mfma_f32_32x32x16_bf16 v[64:79], v[218:221], v[138:141], v[64:79]
	v_add_u32_e32 v161, s42, v174
	ds_read_b64_tr_b16 v[202:203], v161 offset:0
	ds_read_b64_tr_b16 v[204:205], v161 offset:0x800
	ds_read_b64_tr_b16 v[210:211], v161 offset:0x1000
	ds_read_b64_tr_b16 v[212:213], v161 offset:0x1800
	ds_read_b64_tr_b16 v[214:215], v161 offset:0x2000
	ds_read_b64_tr_b16 v[216:217], v161 offset:0x2800
	ds_read_b64_tr_b16 v[218:219], v161 offset:0x3000
	ds_read_b64_tr_b16 v[220:221], v161 offset:0x3800
	v_permlane32_swap_b32_e32 v199, v201
	v_max_f32_e32 v235, v81, v81
	v_max_f32_e32 v237, v80, v80
	v_max_f32_e32 v235, v237, v235
	v_max3_f32 v235, v235, v82, v83
	s_waitcnt lgkmcnt(6)
	v_mfma_f32_32x32x16_bf16 v[0:15], v[194:197], v[202:205], v[0:15]
	ds_read_b64_tr_b16 v[202:203], v161 offset:0x200
	ds_read_b64_tr_b16 v[204:205], v161 offset:0xa00
	v_max3_f32 v235, v235, v84, v85
	v_max3_f32 v235, v235, v86, v87
	v_max3_f32 v235, v235, v88, v89
	v_max3_f32 v235, v235, v90, v91
	v_max3_f32 v235, v235, v92, v93
	v_max3_f32 v235, v235, v94, v95
	s_waitcnt lgkmcnt(6)
	v_mfma_f32_32x32x16_bf16 v[0:15], v[166:169], v[210:213], v[0:15]
	ds_read_b64_tr_b16 v[210:211], v161 offset:0x1200
	ds_read_b64_tr_b16 v[212:213], v161 offset:0x1a00
	v_max3_f32 v235, v235, v64, v65
	v_max3_f32 v235, v235, v66, v67
	v_max3_f32 v235, v235, v68, v69
	v_max3_f32 v235, v235, v70, v71
	v_max3_f32 v235, v235, v72, v73
	v_max3_f32 v235, v235, v74, v75
	s_waitcnt lgkmcnt(6)
	v_mfma_f32_32x32x16_bf16 v[0:15], v[162:165], v[214:217], v[0:15]
	ds_read_b64_tr_b16 v[214:215], v161 offset:0x2200
	ds_read_b64_tr_b16 v[216:217], v161 offset:0x2a00
	v_max3_f32 v235, v235, v76, v77
	v_max3_f32 v235, v235, v78, v79
	v_mov_b32_e32 v237, v235
	s_waitcnt lgkmcnt(6)
	v_mfma_f32_32x32x16_bf16 v[0:15], v[198:201], v[218:221], v[0:15]
	ds_read_b64_tr_b16 v[218:219], v161 offset:0x3200
	ds_read_b64_tr_b16 v[220:221], v161 offset:0x3a00
	v_permlane32_swap_b32_e32 v235, v237
	v_max_f32_e32 v237, v237, v237
	v_max_f32_e32 v235, v235, v235
	s_waitcnt lgkmcnt(6)
	v_mfma_f32_32x32x16_bf16 v[48:63], v[194:197], v[202:205], v[48:63]
	ds_read_b64_tr_b16 v[202:203], v161 offset:0x400
	ds_read_b64_tr_b16 v[204:205], v161 offset:0xc00
	s_waitcnt lgkmcnt(6)
	v_mfma_f32_32x32x16_bf16 v[48:63], v[166:169], v[210:213], v[48:63]
	ds_read_b64_tr_b16 v[210:211], v161 offset:0x1400
	ds_read_b64_tr_b16 v[212:213], v161 offset:0x1c00
	s_waitcnt lgkmcnt(6)
	v_mfma_f32_32x32x16_bf16 v[48:63], v[162:165], v[214:217], v[48:63]
	ds_read_b64_tr_b16 v[214:215], v161 offset:0x2400
	ds_read_b64_tr_b16 v[216:217], v161 offset:0x2c00
	s_waitcnt lgkmcnt(6)
	v_mfma_f32_32x32x16_bf16 v[48:63], v[198:201], v[218:221], v[48:63]
	ds_read_b64_tr_b16 v[218:219], v161 offset:0x3400
	ds_read_b64_tr_b16 v[220:221], v161 offset:0x3c00
	s_waitcnt lgkmcnt(6)
	v_mfma_f32_32x32x16_bf16 v[32:47], v[194:197], v[202:205], v[32:47]
	ds_read_b64_tr_b16 v[202:203], v161 offset:0x600
	ds_read_b64_tr_b16 v[204:205], v161 offset:0xe00
	s_waitcnt lgkmcnt(6)
	v_mfma_f32_32x32x16_bf16 v[32:47], v[166:169], v[210:213], v[32:47]
	ds_read_b64_tr_b16 v[210:211], v161 offset:0x1600
	ds_read_b64_tr_b16 v[212:213], v161 offset:0x1e00
	s_waitcnt lgkmcnt(6)
	v_mfma_f32_32x32x16_bf16 v[32:47], v[162:165], v[214:217], v[32:47]
	ds_read_b64_tr_b16 v[214:215], v161 offset:0x2600
	ds_read_b64_tr_b16 v[216:217], v161 offset:0x2e00
	s_waitcnt lgkmcnt(6)
	v_mfma_f32_32x32x16_bf16 v[32:47], v[198:201], v[218:221], v[32:47]
	ds_read_b64_tr_b16 v[218:219], v161 offset:0x3600
	ds_read_b64_tr_b16 v[220:221], v161 offset:0x3e00
	v_max_f32_e32 v161, v235, v237
	v_sub_f32_e32 v237, v161, v160
	s_waitcnt vmcnt(0)
	s_waitcnt vmcnt(0)
	s_waitcnt lgkmcnt(0)
	s_barrier
; #define SBAR() __builtin_amdgcn_sched_barrier(0)
; template <int OFF> DI s16x4 tr_read(int vb) { s16x4 r; asm volatile("ds_read_b64_tr_b16 %0, %1 offset:%2" : "=&v"(r) : "v"(vb), "i"(OFF) : "memory"); return r; }
; DI void partialSM(f32x16& p0, f32x16& p1, float& m_reg, float& mn, float& alpha) {
;     ...
;   if (__builtin_expect(__all(pmax - m_reg <= ATT_THR / ATT_SCALE), 1)) { mn = m_reg; alpha = 1.f; }
;   else { mn = fmaxf(m_reg, pmax); alpha = __builtin_amdgcn_exp2f((m_reg - mn) * C); m_reg = mn; }
; template <int D0> DI void pv_one(f32x16& od, int vb, bf16x8 pa0, bf16x8 pa1, bf16x8 pa2, bf16x8 pa3) {
;   const s16x4 l0 = tr_read<v_rd_off(D0, 0, 0)>(vb), h0 = tr_read<v_rd_off(D0, 0, 1)>(vb), l1 = tr_read<v_rd_off(D0, 1, 0)>(vb), h1 = tr_read<v_rd_off(D0, 1, 1)>(vb);
;   const s16x4 l2 = tr_read<v_rd_off(D0, 2, 0)>(vb), h2 = tr_read<v_rd_off(D0, 2, 1)>(vb), l3 = tr_read<v_rd_off(D0, 3, 0)>(vb), h3 = tr_read<v_rd_off(D0, 3, 1)>(vb);
;   asm volatile("s_waitcnt lgkmcnt(0)" ::: "memory"); SBAR();
;     ...
;   od = __builtin_amdgcn_mfma_f32_32x32x16_bf16(pa0, PK(l0, h0), od, 0, 0, 0);
;   od = __builtin_amdgcn_mfma_f32_32x32x16_bf16(pa1, PK(l1, h1), od, 0, 0, 0);
;   od = __builtin_amdgcn_mfma_f32_32x32x16_bf16(pa2, PK(l2, h2), od, 0, 0, 0);
;   od = __builtin_amdgcn_mfma_f32_32x32x16_bf16(pa3, PK(l3, h3), od, 0, 0, 0);
;     ...
; }
; DI void pv_d0(f32x16* o, int vb, bf16x8 pa0, bf16x8 pa1, bf16x8 pa2, bf16x8 pa3) {
;   pv_one<0>(o[0], vb, pa0, pa1, pa2, pa3); pv_one<1>(o[1], vb, pa0, pa1, pa2, pa3); pv_one<2>(o[2], vb, pa0, pa1, pa2, pa3); pv_one<3>(o[3], vb, pa0, pa1, pa2, pa3);
	v_mfma_f32_32x32x16_bf16 v[16:31], v[194:197], v[202:205], v[16:31]
	v_mfma_f32_32x32x16_bf16 v[16:31], v[166:169], v[210:213], v[16:31]
	v_mfma_f32_32x32x16_bf16 v[16:31], v[162:165], v[214:217], v[16:31]
	v_mfma_f32_32x32x16_bf16 v[16:31], v[198:201], v[218:221], v[16:31]
	v_cmp_ge_f32_e32 vcc, s65, v237
	s_cmp_eq_u64 vcc, exec
	s_cselect_b64 s[38:39], -1, 0
	s_cmp_ge_u32 s12, s52
	s_cselect_b64 s[42:43], -1, 0
	s_and_b64 vcc, exec, s[42:43]
	s_branch .Lattn_bb2_join
